# mLSTM: reduce-scatter reduction (5 DPP adds + 1 DPP mov, lane-0 store), next-token LDS reads as wait-state fillers, staged waits
# speedup vs baseline: 1.0006x; 1.0006x over previous
.Lml2_nsc1:
	v_add_u32_e32 v64, s20, v69
	v_add_u32_e32 v65, s20, v70
	v_add_u32_e32 v66, s20, v71
	v_add_u32_e32 v67, s20, v72
	v_add_u32_e32 v68, s20, v73
	v_add_u32_e32 v58, s18, v2
	v_add_u32_e32 v59, s18, v3
	v_mov_b32_e32 v60, s18
	v_add_u32_e32 v61, s19, v2
	v_add_u32_e32 v62, s19, v3
	v_mov_b32_e32 v63, s19
	v_mov_b32_e32 v6, 0
	v_mov_b32_e32 v7, 0
	v_mov_b32_e32 v8, 0
	v_mov_b32_e32 v9, 0
	v_mov_b32_e32 v10, 0
	v_mov_b32_e32 v11, 0
	v_mov_b32_e32 v12, 0
	v_mov_b32_e32 v13, 0
	v_mov_b32_e32 v14, 0
	v_mov_b32_e32 v15, 0
	v_mov_b32_e32 v16, 0
	v_mov_b32_e32 v17, 0
	s_mov_b32 s16, 0
	s_waitcnt vmcnt(0) lgkmcnt(0)
	s_barrier
	s_mov_b32 s18, 0x10001
	s_mov_b32 s19, 0x10001
	ds_read_b128 v[30:33], v2 offset:8448
	ds_read_b128 v[34:37], v2 offset:8704
	ds_read_b64 v[38:39], v3 offset:12544
	ds_read_b128 v[40:43], v1 offset:14848

.Lml2_nsl2:
	s_add_u32 s22, s22, 0x400
	s_addc_u32 s23, s23, 0
	s_add_u32 s8, s8, 0xc000
	s_addc_u32 s9, s9, 0
	s_add_u32 s10, s10, 0x20000
	s_addc_u32 s11, s11, 0
	s_add_u32 s12, s12, 0x400
	s_addc_u32 s13, s13, 0
	s_waitcnt lgkmcnt(2)
	v_pk_mul_f32 v[18:19], v[30:31], v[40:41] op_sel:[0,1] op_sel_hi:[1,1]
	v_pk_mul_f32 v[20:21], v[32:33], v[40:41] op_sel:[0,1] op_sel_hi:[1,1]
	s_waitcnt lgkmcnt(1)
	v_pk_mul_f32 v[22:23], v[38:39], v[18:19] op_sel:[0,0] op_sel_hi:[1,0]
	v_pk_fma_f32 v[6:7], v[6:7], v[40:41], v[22:23] op_sel_hi:[1,0,1]
	s_waitcnt lgkmcnt(0)
	v_pk_mul_f32 v[26:27], v[6:7], v[34:35] op_sel_hi:[1,0]
	v_pk_mul_f32 v[24:25], v[38:39], v[18:19] op_sel:[0,1] op_sel_hi:[1,1]
	v_pk_fma_f32 v[8:9], v[8:9], v[40:41], v[24:25] op_sel_hi:[1,0,1]
	v_pk_fma_f32 v[26:27], v[8:9], v[34:35], v[26:27] op_sel:[0,1,0] op_sel_hi:[1,1,1]
	v_pk_mul_f32 v[22:23], v[38:39], v[20:21] op_sel:[0,0] op_sel_hi:[1,0]
	v_pk_fma_f32 v[10:11], v[10:11], v[40:41], v[22:23] op_sel_hi:[1,0,1]
	v_pk_fma_f32 v[26:27], v[10:11], v[36:37], v[26:27] op_sel:[0,0,0] op_sel_hi:[1,0,1]
	v_pk_mul_f32 v[24:25], v[38:39], v[20:21] op_sel:[0,1] op_sel_hi:[1,1]
	v_pk_fma_f32 v[12:13], v[12:13], v[40:41], v[24:25] op_sel_hi:[1,0,1]
	v_pk_fma_f32 v[26:27], v[12:13], v[36:37], v[26:27] op_sel:[0,1,0] op_sel_hi:[1,1,1]
	v_pk_fma_f32 v[14:15], v[14:15], v[40:41], v[18:19] op_sel_hi:[1,0,1]
	v_pk_fma_f32 v[16:17], v[16:17], v[40:41], v[20:21] op_sel_hi:[1,0,1]
	v_add_f32_dpp v26, v26, v26 row_ror:8 row_mask:0xf bank_mask:0x3 bound_ctrl:1
	v_add_f32_dpp v26, v27, v27 row_ror:8 row_mask:0xf bank_mask:0xc bound_ctrl:1
	ds_read_b128 v[54:57], v1 offset:14864
	ds_read_b128 v[44:47], v2 offset:8960
	v_add_f32_dpp v26, v26, v26 row_half_mirror row_mask:0xf bank_mask:0xf bound_ctrl:1
	ds_read_b64 v[52:53], v3 offset:12800
	ds_read_b128 v[48:51], v2 offset:9216
	v_add_f32_dpp v26, v26, v26 quad_perm:[1,0,3,2] row_mask:0xf bank_mask:0xf bound_ctrl:1
	s_add_u32 s14, s14, 0x1000
	s_addc_u32 s15, s15, 0
	v_add_f32_dpp v26, v26, v26 quad_perm:[2,3,0,1] row_mask:0xf bank_mask:0xf bound_ctrl:1
	s_cmp_eq_u32 s21, 0
	s_cbranch_scc1 .Lml2_den0_0
.Lml2_back0_0:
	v_mov_b32_dpp v27, v26 row_ror:8 row_mask:0xf bank_mask:0xf bound_ctrl:1
	s_mov_b64 exec, s[18:19]
	v_cvt_pk_bf16_f32 v28, v26, v27
	global_store_dword v4, v28, s[14:15] offset:-4096
	s_mov_b64 exec, -1
	s_waitcnt lgkmcnt(2)
	v_pk_mul_f32 v[18:19], v[44:45], v[54:55] op_sel:[0,1] op_sel_hi:[1,1]
	v_pk_mul_f32 v[20:21], v[46:47], v[54:55] op_sel:[0,1] op_sel_hi:[1,1]
	s_waitcnt lgkmcnt(1)
	v_pk_mul_f32 v[22:23], v[52:53], v[18:19] op_sel:[0,0] op_sel_hi:[1,0]
	v_pk_fma_f32 v[6:7], v[6:7], v[54:55], v[22:23] op_sel_hi:[1,0,1]
	s_waitcnt lgkmcnt(0)
	v_pk_mul_f32 v[26:27], v[6:7], v[48:49] op_sel_hi:[1,0]
	v_pk_mul_f32 v[24:25], v[52:53], v[18:19] op_sel:[0,1] op_sel_hi:[1,1]
	v_pk_fma_f32 v[8:9], v[8:9], v[54:55], v[24:25] op_sel_hi:[1,0,1]
	v_pk_fma_f32 v[26:27], v[8:9], v[48:49], v[26:27] op_sel:[0,1,0] op_sel_hi:[1,1,1]
	v_pk_mul_f32 v[22:23], v[52:53], v[20:21] op_sel:[0,0] op_sel_hi:[1,0]
	v_pk_fma_f32 v[10:11], v[10:11], v[54:55], v[22:23] op_sel_hi:[1,0,1]
	v_pk_fma_f32 v[26:27], v[10:11], v[50:51], v[26:27] op_sel:[0,0,0] op_sel_hi:[1,0,1]
	v_pk_mul_f32 v[24:25], v[52:53], v[20:21] op_sel:[0,1] op_sel_hi:[1,1]
	v_pk_fma_f32 v[12:13], v[12:13], v[54:55], v[24:25] op_sel_hi:[1,0,1]
	v_pk_fma_f32 v[26:27], v[12:13], v[50:51], v[26:27] op_sel:[0,1,0] op_sel_hi:[1,1,1]
	v_pk_fma_f32 v[14:15], v[14:15], v[54:55], v[18:19] op_sel_hi:[1,0,1]
	v_pk_fma_f32 v[16:17], v[16:17], v[54:55], v[20:21] op_sel_hi:[1,0,1]
	v_add_f32_dpp v26, v26, v26 row_ror:8 row_mask:0xf bank_mask:0x3 bound_ctrl:1
	v_add_f32_dpp v26, v27, v27 row_ror:8 row_mask:0xf bank_mask:0xc bound_ctrl:1
	ds_read_b128 v[40:43], v1 offset:14880
	ds_read_b128 v[30:33], v2 offset:9472
	v_add_f32_dpp v26, v26, v26 row_half_mirror row_mask:0xf bank_mask:0xf bound_ctrl:1
	ds_read_b64 v[38:39], v3 offset:13056
	ds_read_b128 v[34:37], v2 offset:9728
	v_add_f32_dpp v26, v26, v26 quad_perm:[1,0,3,2] row_mask:0xf bank_mask:0xf bound_ctrl:1
	s_add_u32 s14, s14, 0x1000
	s_addc_u32 s15, s15, 0
	v_add_f32_dpp v26, v26, v26 quad_perm:[2,3,0,1] row_mask:0xf bank_mask:0xf bound_ctrl:1
	s_cmp_eq_u32 s21, 1
	s_cbranch_scc1 .Lml2_den0_1
.Lml2_back0_1:
	v_mov_b32_dpp v27, v26 row_ror:8 row_mask:0xf bank_mask:0xf bound_ctrl:1
	s_mov_b64 exec, s[18:19]
	v_cvt_pk_bf16_f32 v28, v26, v27
	global_store_dword v4, v28, s[14:15] offset:-4096
	s_mov_b64 exec, -1
	s_waitcnt lgkmcnt(2)
	v_pk_mul_f32 v[18:19], v[30:31], v[40:41] op_sel:[0,1] op_sel_hi:[1,1]
	v_pk_mul_f32 v[20:21], v[32:33], v[40:41] op_sel:[0,1] op_sel_hi:[1,1]
	s_waitcnt lgkmcnt(1)
	v_pk_mul_f32 v[22:23], v[38:39], v[18:19] op_sel:[0,0] op_sel_hi:[1,0]
	v_pk_fma_f32 v[6:7], v[6:7], v[40:41], v[22:23] op_sel_hi:[1,0,1]
	s_waitcnt lgkmcnt(0)
	v_pk_mul_f32 v[26:27], v[6:7], v[34:35] op_sel_hi:[1,0]
	v_pk_mul_f32 v[24:25], v[38:39], v[18:19] op_sel:[0,1] op_sel_hi:[1,1]
	v_pk_fma_f32 v[8:9], v[8:9], v[40:41], v[24:25] op_sel_hi:[1,0,1]
	v_pk_fma_f32 v[26:27], v[8:9], v[34:35], v[26:27] op_sel:[0,1,0] op_sel_hi:[1,1,1]
	v_pk_mul_f32 v[22:23], v[38:39], v[20:21] op_sel:[0,0] op_sel_hi:[1,0]
	v_pk_fma_f32 v[10:11], v[10:11], v[40:41], v[22:23] op_sel_hi:[1,0,1]
	v_pk_fma_f32 v[26:27], v[10:11], v[36:37], v[26:27] op_sel:[0,0,0] op_sel_hi:[1,0,1]
	v_pk_mul_f32 v[24:25], v[38:39], v[20:21] op_sel:[0,1] op_sel_hi:[1,1]
	v_pk_fma_f32 v[12:13], v[12:13], v[40:41], v[24:25] op_sel_hi:[1,0,1]
	v_pk_fma_f32 v[26:27], v[12:13], v[36:37], v[26:27] op_sel:[0,1,0] op_sel_hi:[1,1,1]
	v_pk_fma_f32 v[14:15], v[14:15], v[40:41], v[18:19] op_sel_hi:[1,0,1]
	v_pk_fma_f32 v[16:17], v[16:17], v[40:41], v[20:21] op_sel_hi:[1,0,1]
	v_add_f32_dpp v26, v26, v26 row_ror:8 row_mask:0xf bank_mask:0x3 bound_ctrl:1
	v_add_f32_dpp v26, v27, v27 row_ror:8 row_mask:0xf bank_mask:0xc bound_ctrl:1
	ds_read_b128 v[54:57], v1 offset:14896
	ds_read_b128 v[44:47], v2 offset:9984
	v_add_f32_dpp v26, v26, v26 row_half_mirror row_mask:0xf bank_mask:0xf bound_ctrl:1
	ds_read_b64 v[52:53], v3 offset:13312
	ds_read_b128 v[48:51], v2 offset:10240
	v_add_f32_dpp v26, v26, v26 quad_perm:[1,0,3,2] row_mask:0xf bank_mask:0xf bound_ctrl:1
	s_add_u32 s14, s14, 0x1000
	s_addc_u32 s15, s15, 0
	v_add_f32_dpp v26, v26, v26 quad_perm:[2,3,0,1] row_mask:0xf bank_mask:0xf bound_ctrl:1
	s_cmp_eq_u32 s21, 2
	s_cbranch_scc1 .Lml2_den0_2
.Lml2_back0_2:
	v_mov_b32_dpp v27, v26 row_ror:8 row_mask:0xf bank_mask:0xf bound_ctrl:1
	s_mov_b64 exec, s[18:19]
	v_cvt_pk_bf16_f32 v28, v26, v27
	global_store_dword v4, v28, s[14:15] offset:-4096
	s_mov_b64 exec, -1
	s_waitcnt lgkmcnt(2)
	v_pk_mul_f32 v[18:19], v[44:45], v[54:55] op_sel:[0,1] op_sel_hi:[1,1]
	v_pk_mul_f32 v[20:21], v[46:47], v[54:55] op_sel:[0,1] op_sel_hi:[1,1]
	s_waitcnt lgkmcnt(1)
	v_pk_mul_f32 v[22:23], v[52:53], v[18:19] op_sel:[0,0] op_sel_hi:[1,0]
	v_pk_fma_f32 v[6:7], v[6:7], v[54:55], v[22:23] op_sel_hi:[1,0,1]
	s_waitcnt lgkmcnt(0)
	v_pk_mul_f32 v[26:27], v[6:7], v[48:49] op_sel_hi:[1,0]
	v_pk_mul_f32 v[24:25], v[52:53], v[18:19] op_sel:[0,1] op_sel_hi:[1,1]
	v_pk_fma_f32 v[8:9], v[8:9], v[54:55], v[24:25] op_sel_hi:[1,0,1]
	v_pk_fma_f32 v[26:27], v[8:9], v[48:49], v[26:27] op_sel:[0,1,0] op_sel_hi:[1,1,1]
	v_pk_mul_f32 v[22:23], v[52:53], v[20:21] op_sel:[0,0] op_sel_hi:[1,0]
	v_pk_fma_f32 v[10:11], v[10:11], v[54:55], v[22:23] op_sel_hi:[1,0,1]
	v_pk_fma_f32 v[26:27], v[10:11], v[50:51], v[26:27] op_sel:[0,0,0] op_sel_hi:[1,0,1]
	v_pk_mul_f32 v[24:25], v[52:53], v[20:21] op_sel:[0,1] op_sel_hi:[1,1]
	v_pk_fma_f32 v[12:13], v[12:13], v[54:55], v[24:25] op_sel_hi:[1,0,1]
	v_pk_fma_f32 v[26:27], v[12:13], v[50:51], v[26:27] op_sel:[0,1,0] op_sel_hi:[1,1,1]
	v_pk_fma_f32 v[14:15], v[14:15], v[54:55], v[18:19] op_sel_hi:[1,0,1]
	v_pk_fma_f32 v[16:17], v[16:17], v[54:55], v[20:21] op_sel_hi:[1,0,1]
	v_add_f32_dpp v26, v26, v26 row_ror:8 row_mask:0xf bank_mask:0x3 bound_ctrl:1
	v_add_f32_dpp v26, v27, v27 row_ror:8 row_mask:0xf bank_mask:0xc bound_ctrl:1
	ds_read_b128 v[40:43], v1 offset:14912
	ds_read_b128 v[30:33], v2 offset:10496
	v_add_f32_dpp v26, v26, v26 row_half_mirror row_mask:0xf bank_mask:0xf bound_ctrl:1
	ds_read_b64 v[38:39], v3 offset:13568
	ds_read_b128 v[34:37], v2 offset:10752
	v_add_f32_dpp v26, v26, v26 quad_perm:[1,0,3,2] row_mask:0xf bank_mask:0xf bound_ctrl:1
	s_add_u32 s14, s14, 0x1000
	s_addc_u32 s15, s15, 0
	v_add_f32_dpp v26, v26, v26 quad_perm:[2,3,0,1] row_mask:0xf bank_mask:0xf bound_ctrl:1
	s_cmp_eq_u32 s21, 3
	s_cbranch_scc1 .Lml2_den0_3
.Lml2_back0_3:
	v_mov_b32_dpp v27, v26 row_ror:8 row_mask:0xf bank_mask:0xf bound_ctrl:1
	s_mov_b64 exec, s[18:19]
	v_cvt_pk_bf16_f32 v28, v26, v27
	global_store_dword v4, v28, s[14:15] offset:-4096
	s_mov_b64 exec, -1
	s_waitcnt lgkmcnt(2)
	v_pk_mul_f32 v[18:19], v[30:31], v[40:41] op_sel:[0,1] op_sel_hi:[1,1]
	v_pk_mul_f32 v[20:21], v[32:33], v[40:41] op_sel:[0,1] op_sel_hi:[1,1]
	s_waitcnt lgkmcnt(1)
	v_pk_mul_f32 v[22:23], v[38:39], v[18:19] op_sel:[0,0] op_sel_hi:[1,0]
	v_pk_fma_f32 v[6:7], v[6:7], v[40:41], v[22:23] op_sel_hi:[1,0,1]
	s_waitcnt lgkmcnt(0)
	v_pk_mul_f32 v[26:27], v[6:7], v[34:35] op_sel_hi:[1,0]
	v_pk_mul_f32 v[24:25], v[38:39], v[18:19] op_sel:[0,1] op_sel_hi:[1,1]
	v_pk_fma_f32 v[8:9], v[8:9], v[40:41], v[24:25] op_sel_hi:[1,0,1]
	v_pk_fma_f32 v[26:27], v[8:9], v[34:35], v[26:27] op_sel:[0,1,0] op_sel_hi:[1,1,1]
	v_pk_mul_f32 v[22:23], v[38:39], v[20:21] op_sel:[0,0] op_sel_hi:[1,0]
	v_pk_fma_f32 v[10:11], v[10:11], v[40:41], v[22:23] op_sel_hi:[1,0,1]
	v_pk_fma_f32 v[26:27], v[10:11], v[36:37], v[26:27] op_sel:[0,0,0] op_sel_hi:[1,0,1]
	v_pk_mul_f32 v[24:25], v[38:39], v[20:21] op_sel:[0,1] op_sel_hi:[1,1]
	v_pk_fma_f32 v[12:13], v[12:13], v[40:41], v[24:25] op_sel_hi:[1,0,1]
	v_pk_fma_f32 v[26:27], v[12:13], v[36:37], v[26:27] op_sel:[0,1,0] op_sel_hi:[1,1,1]
	v_pk_fma_f32 v[14:15], v[14:15], v[40:41], v[18:19] op_sel_hi:[1,0,1]
	v_pk_fma_f32 v[16:17], v[16:17], v[40:41], v[20:21] op_sel_hi:[1,0,1]
	v_add_f32_dpp v26, v26, v26 row_ror:8 row_mask:0xf bank_mask:0x3 bound_ctrl:1
	v_add_f32_dpp v26, v27, v27 row_ror:8 row_mask:0xf bank_mask:0xc bound_ctrl:1
	ds_read_b128 v[54:57], v1 offset:14928
	ds_read_b128 v[44:47], v2 offset:11008
	v_add_f32_dpp v26, v26, v26 row_half_mirror row_mask:0xf bank_mask:0xf bound_ctrl:1
	ds_read_b64 v[52:53], v3 offset:13824
	ds_read_b128 v[48:51], v2 offset:11264
	v_add_f32_dpp v26, v26, v26 quad_perm:[1,0,3,2] row_mask:0xf bank_mask:0xf bound_ctrl:1
	s_add_u32 s14, s14, 0x1000
	s_addc_u32 s15, s15, 0
	v_add_f32_dpp v26, v26, v26 quad_perm:[2,3,0,1] row_mask:0xf bank_mask:0xf bound_ctrl:1
	s_cmp_eq_u32 s21, 4
	s_cbranch_scc1 .Lml2_den0_4
.Lml2_back0_4:
	v_mov_b32_dpp v27, v26 row_ror:8 row_mask:0xf bank_mask:0xf bound_ctrl:1
	s_mov_b64 exec, s[18:19]
	v_cvt_pk_bf16_f32 v28, v26, v27
	global_store_dword v4, v28, s[14:15] offset:-4096
	s_mov_b64 exec, -1
	s_waitcnt lgkmcnt(2)
	v_pk_mul_f32 v[18:19], v[44:45], v[54:55] op_sel:[0,1] op_sel_hi:[1,1]
	v_pk_mul_f32 v[20:21], v[46:47], v[54:55] op_sel:[0,1] op_sel_hi:[1,1]
	s_waitcnt lgkmcnt(1)
	v_pk_mul_f32 v[22:23], v[52:53], v[18:19] op_sel:[0,0] op_sel_hi:[1,0]
	v_pk_fma_f32 v[6:7], v[6:7], v[54:55], v[22:23] op_sel_hi:[1,0,1]
	s_waitcnt lgkmcnt(0)
	v_pk_mul_f32 v[26:27], v[6:7], v[48:49] op_sel_hi:[1,0]
	v_pk_mul_f32 v[24:25], v[52:53], v[18:19] op_sel:[0,1] op_sel_hi:[1,1]
	v_pk_fma_f32 v[8:9], v[8:9], v[54:55], v[24:25] op_sel_hi:[1,0,1]
	v_pk_fma_f32 v[26:27], v[8:9], v[48:49], v[26:27] op_sel:[0,1,0] op_sel_hi:[1,1,1]
	v_pk_mul_f32 v[22:23], v[52:53], v[20:21] op_sel:[0,0] op_sel_hi:[1,0]
	v_pk_fma_f32 v[10:11], v[10:11], v[54:55], v[22:23] op_sel_hi:[1,0,1]
	v_pk_fma_f32 v[26:27], v[10:11], v[50:51], v[26:27] op_sel:[0,0,0] op_sel_hi:[1,0,1]
	v_pk_mul_f32 v[24:25], v[52:53], v[20:21] op_sel:[0,1] op_sel_hi:[1,1]
	v_pk_fma_f32 v[12:13], v[12:13], v[54:55], v[24:25] op_sel_hi:[1,0,1]
	v_pk_fma_f32 v[26:27], v[12:13], v[50:51], v[26:27] op_sel:[0,1,0] op_sel_hi:[1,1,1]
	v_pk_fma_f32 v[14:15], v[14:15], v[54:55], v[18:19] op_sel_hi:[1,0,1]
	v_pk_fma_f32 v[16:17], v[16:17], v[54:55], v[20:21] op_sel_hi:[1,0,1]
	v_add_f32_dpp v26, v26, v26 row_ror:8 row_mask:0xf bank_mask:0x3 bound_ctrl:1
	v_add_f32_dpp v26, v27, v27 row_ror:8 row_mask:0xf bank_mask:0xc bound_ctrl:1
	ds_read_b128 v[40:43], v1 offset:14944
	ds_read_b128 v[30:33], v2 offset:11520
	v_add_f32_dpp v26, v26, v26 row_half_mirror row_mask:0xf bank_mask:0xf bound_ctrl:1
	ds_read_b64 v[38:39], v3 offset:14080
	ds_read_b128 v[34:37], v2 offset:11776
	v_add_f32_dpp v26, v26, v26 quad_perm:[1,0,3,2] row_mask:0xf bank_mask:0xf bound_ctrl:1
	s_add_u32 s14, s14, 0x1000
	s_addc_u32 s15, s15, 0
	v_add_f32_dpp v26, v26, v26 quad_perm:[2,3,0,1] row_mask:0xf bank_mask:0xf bound_ctrl:1
	s_cmp_eq_u32 s21, 5
	s_cbranch_scc1 .Lml2_den0_5
.Lml2_back0_5:
	v_mov_b32_dpp v27, v26 row_ror:8 row_mask:0xf bank_mask:0xf bound_ctrl:1
	s_mov_b64 exec, s[18:19]
	v_cvt_pk_bf16_f32 v28, v26, v27
	global_store_dword v4, v28, s[14:15] offset:-4096
	s_mov_b64 exec, -1
	s_waitcnt lgkmcnt(2)
	v_pk_mul_f32 v[18:19], v[30:31], v[40:41] op_sel:[0,1] op_sel_hi:[1,1]
	v_pk_mul_f32 v[20:21], v[32:33], v[40:41] op_sel:[0,1] op_sel_hi:[1,1]
	s_waitcnt lgkmcnt(1)
	v_pk_mul_f32 v[22:23], v[38:39], v[18:19] op_sel:[0,0] op_sel_hi:[1,0]
	v_pk_fma_f32 v[6:7], v[6:7], v[40:41], v[22:23] op_sel_hi:[1,0,1]
	s_waitcnt lgkmcnt(0)
	v_pk_mul_f32 v[26:27], v[6:7], v[34:35] op_sel_hi:[1,0]
	v_pk_mul_f32 v[24:25], v[38:39], v[18:19] op_sel:[0,1] op_sel_hi:[1,1]
	v_pk_fma_f32 v[8:9], v[8:9], v[40:41], v[24:25] op_sel_hi:[1,0,1]
	v_pk_fma_f32 v[26:27], v[8:9], v[34:35], v[26:27] op_sel:[0,1,0] op_sel_hi:[1,1,1]
	v_pk_mul_f32 v[22:23], v[38:39], v[20:21] op_sel:[0,0] op_sel_hi:[1,0]
	v_pk_fma_f32 v[10:11], v[10:11], v[40:41], v[22:23] op_sel_hi:[1,0,1]
	v_pk_fma_f32 v[26:27], v[10:11], v[36:37], v[26:27] op_sel:[0,0,0] op_sel_hi:[1,0,1]
	v_pk_mul_f32 v[24:25], v[38:39], v[20:21] op_sel:[0,1] op_sel_hi:[1,1]
	v_pk_fma_f32 v[12:13], v[12:13], v[40:41], v[24:25] op_sel_hi:[1,0,1]
	v_pk_fma_f32 v[26:27], v[12:13], v[36:37], v[26:27] op_sel:[0,1,0] op_sel_hi:[1,1,1]
	v_pk_fma_f32 v[14:15], v[14:15], v[40:41], v[18:19] op_sel_hi:[1,0,1]
	v_pk_fma_f32 v[16:17], v[16:17], v[40:41], v[20:21] op_sel_hi:[1,0,1]
	v_add_f32_dpp v26, v26, v26 row_ror:8 row_mask:0xf bank_mask:0x3 bound_ctrl:1
	v_add_f32_dpp v26, v27, v27 row_ror:8 row_mask:0xf bank_mask:0xc bound_ctrl:1
	ds_read_b128 v[54:57], v1 offset:14960
	ds_read_b128 v[44:47], v2 offset:12032
	v_add_f32_dpp v26, v26, v26 row_half_mirror row_mask:0xf bank_mask:0xf bound_ctrl:1
	ds_read_b64 v[52:53], v3 offset:14336
	ds_read_b128 v[48:51], v2 offset:12288
	v_add_f32_dpp v26, v26, v26 quad_perm:[1,0,3,2] row_mask:0xf bank_mask:0xf bound_ctrl:1
	s_add_u32 s14, s14, 0x1000
	s_addc_u32 s15, s15, 0
	v_add_f32_dpp v26, v26, v26 quad_perm:[2,3,0,1] row_mask:0xf bank_mask:0xf bound_ctrl:1
	s_cmp_eq_u32 s21, 6
	s_cbranch_scc1 .Lml2_den0_6
.Lml2_back0_6:
	v_mov_b32_dpp v27, v26 row_ror:8 row_mask:0xf bank_mask:0xf bound_ctrl:1
	s_mov_b64 exec, s[18:19]
	v_cvt_pk_bf16_f32 v28, v26, v27
	global_store_dword v4, v28, s[14:15] offset:-4096
	s_mov_b64 exec, -1
	s_waitcnt lgkmcnt(2)
	v_pk_mul_f32 v[18:19], v[44:45], v[54:55] op_sel:[0,1] op_sel_hi:[1,1]
	v_pk_mul_f32 v[20:21], v[46:47], v[54:55] op_sel:[0,1] op_sel_hi:[1,1]
	s_waitcnt lgkmcnt(1)
	v_pk_mul_f32 v[22:23], v[52:53], v[18:19] op_sel:[0,0] op_sel_hi:[1,0]
	v_pk_fma_f32 v[6:7], v[6:7], v[54:55], v[22:23] op_sel_hi:[1,0,1]
	s_waitcnt lgkmcnt(0)
	v_pk_mul_f32 v[26:27], v[6:7], v[48:49] op_sel_hi:[1,0]
	v_pk_mul_f32 v[24:25], v[52:53], v[18:19] op_sel:[0,1] op_sel_hi:[1,1]
	v_pk_fma_f32 v[8:9], v[8:9], v[54:55], v[24:25] op_sel_hi:[1,0,1]
	v_pk_fma_f32 v[26:27], v[8:9], v[48:49], v[26:27] op_sel:[0,1,0] op_sel_hi:[1,1,1]
	v_pk_mul_f32 v[22:23], v[52:53], v[20:21] op_sel:[0,0] op_sel_hi:[1,0]
	v_pk_fma_f32 v[10:11], v[10:11], v[54:55], v[22:23] op_sel_hi:[1,0,1]
	v_pk_fma_f32 v[26:27], v[10:11], v[50:51], v[26:27] op_sel:[0,0,0] op_sel_hi:[1,0,1]
	v_pk_mul_f32 v[24:25], v[52:53], v[20:21] op_sel:[0,1] op_sel_hi:[1,1]
	v_pk_fma_f32 v[12:13], v[12:13], v[54:55], v[24:25] op_sel_hi:[1,0,1]
	v_pk_fma_f32 v[26:27], v[12:13], v[50:51], v[26:27] op_sel:[0,1,0] op_sel_hi:[1,1,1]
	v_pk_fma_f32 v[14:15], v[14:15], v[54:55], v[18:19] op_sel_hi:[1,0,1]
	v_pk_fma_f32 v[16:17], v[16:17], v[54:55], v[20:21] op_sel_hi:[1,0,1]
	v_add_f32_dpp v26, v26, v26 row_ror:8 row_mask:0xf bank_mask:0x3 bound_ctrl:1
	v_add_f32_dpp v26, v27, v27 row_ror:8 row_mask:0xf bank_mask:0xc bound_ctrl:1
	ds_read_b128 v[40:43], v1 offset:31232
	ds_read_b128 v[30:33], v2 offset:24832
	v_add_f32_dpp v26, v26, v26 row_half_mirror row_mask:0xf bank_mask:0xf bound_ctrl:1
	ds_read_b64 v[38:39], v3 offset:28928
	ds_read_b128 v[34:37], v2 offset:25088
	v_add_f32_dpp v26, v26, v26 quad_perm:[1,0,3,2] row_mask:0xf bank_mask:0xf bound_ctrl:1
	s_add_u32 s14, s14, 0x1000
	s_addc_u32 s15, s15, 0
	v_add_f32_dpp v26, v26, v26 quad_perm:[2,3,0,1] row_mask:0xf bank_mask:0xf bound_ctrl:1
	s_cmp_eq_u32 s21, 7
	s_cbranch_scc1 .Lml2_den0_7
.Lml2_back0_7:
	v_mov_b32_dpp v27, v26 row_ror:8 row_mask:0xf bank_mask:0xf bound_ctrl:1
	s_mov_b64 exec, s[18:19]
	v_cvt_pk_bf16_f32 v28, v26, v27
	global_store_dword v4, v28, s[14:15] offset:-4096
	s_mov_b64 exec, -1
	s_waitcnt vmcnt(8)
	v_lshlrev_b32_e32 v88, 16, v80
	v_lshlrev_b32_e32 v89, 16, v81
	v_and_b32_e32 v90, s17, v80
	v_and_b32_e32 v91, s17, v81
	v_lshlrev_b32_e32 v92, 16, v82
	v_and_b32_e32 v93, s17, v82
	v_lshlrev_b32_e32 v94, 16, v83
	v_and_b32_e32 v95, s17, v83
	v_lshlrev_b32_e32 v96, 16, v84
	v_and_b32_e32 v97, s17, v84
	ds_write_b128 v69, v[88:91] offset:33024
	ds_write_b64 v70, v[92:93] offset:33024
	ds_write_b64 v71, v[94:95] offset:33024
	ds_write_b64 v71, v[96:97] offset:33152
	ds_write_b32 v72, v85 offset:33024
	s_cmp_lg_u32 s36, 4
	s_cbranch_scc1 .Lml2_nsc2
	v_mov_b32_e32 v98, v87
	s_nop 1
	v_add_f32_dpp v98, v98, v98 row_shr:1 row_mask:0xf bank_mask:0xf bound_ctrl:1
	s_nop 1
	v_add_f32_dpp v98, v98, v98 row_shr:2 row_mask:0xf bank_mask:0xf bound_ctrl:1
	s_nop 1
	v_add_f32_dpp v98, v98, v98 row_shr:4 row_mask:0xf bank_mask:0xf bound_ctrl:1
	s_nop 1
	v_sub_f32_e32 v99, v86, v98
	s_nop 1
	v_max_f32_dpp v99, v99, v99 row_shr:1 row_mask:0xf bank_mask:0xf
	s_nop 1
	v_max_f32_dpp v99, v99, v99 row_shr:2 row_mask:0xf bank_mask:0xf
	s_nop 1
	v_max_f32_dpp v99, v99, v99 row_shr:4 row_mask:0xf bank_mask:0xf
	s_nop 1
	v_max_f32_e32 v99, v99, v0
	v_add_f32_e32 v103, v98, v99
	v_mov_b32_e32 v105, v0
	s_nop 1
	v_mov_b32_dpp v105, v103 row_shr:1 row_mask:0xf bank_mask:0xf
	v_sub_f32_e32 v104, v86, v103
	v_add_f32_e32 v105, v87, v105
	v_fma_f32 v104, v104, s29, v29
	v_sub_f32_e32 v105, v105, v103
	v_exp_f32_e32 v101, v104
	v_mul_f32_e32 v105, s29, v105
	v_mul_f32_e32 v104, 0xbfb8aa3b, v103
	v_exp_f32_e32 v100, v105
	v_exp_f32_e32 v102, v104
	v_readlane_b32 s4, v103, 7
	s_nop 3
	v_mov_b32_e32 v0, s4
	ds_write_b128 v73, v[100:103] offset:33024

.Lml2_nsl3:
	s_add_u32 s22, s22, 0x400
	s_addc_u32 s23, s23, 0
	s_add_u32 s8, s8, 0xc000
	s_addc_u32 s9, s9, 0
	s_add_u32 s10, s10, 0x20000
	s_addc_u32 s11, s11, 0
	s_add_u32 s12, s12, 0x400
	s_addc_u32 s13, s13, 0
	s_waitcnt lgkmcnt(2)
	v_pk_mul_f32 v[18:19], v[30:31], v[40:41] op_sel:[0,1] op_sel_hi:[1,1]
	v_pk_mul_f32 v[20:21], v[32:33], v[40:41] op_sel:[0,1] op_sel_hi:[1,1]
	s_waitcnt lgkmcnt(1)
	v_pk_mul_f32 v[22:23], v[38:39], v[18:19] op_sel:[0,0] op_sel_hi:[1,0]
	v_pk_fma_f32 v[6:7], v[6:7], v[40:41], v[22:23] op_sel_hi:[1,0,1]
	s_waitcnt lgkmcnt(0)
	v_pk_mul_f32 v[26:27], v[6:7], v[34:35] op_sel_hi:[1,0]
	v_pk_mul_f32 v[24:25], v[38:39], v[18:19] op_sel:[0,1] op_sel_hi:[1,1]
	v_pk_fma_f32 v[8:9], v[8:9], v[40:41], v[24:25] op_sel_hi:[1,0,1]
	v_pk_fma_f32 v[26:27], v[8:9], v[34:35], v[26:27] op_sel:[0,1,0] op_sel_hi:[1,1,1]
	v_pk_mul_f32 v[22:23], v[38:39], v[20:21] op_sel:[0,0] op_sel_hi:[1,0]
	v_pk_fma_f32 v[10:11], v[10:11], v[40:41], v[22:23] op_sel_hi:[1,0,1]
	v_pk_fma_f32 v[26:27], v[10:11], v[36:37], v[26:27] op_sel:[0,0,0] op_sel_hi:[1,0,1]
	v_pk_mul_f32 v[24:25], v[38:39], v[20:21] op_sel:[0,1] op_sel_hi:[1,1]
	v_pk_fma_f32 v[12:13], v[12:13], v[40:41], v[24:25] op_sel_hi:[1,0,1]
	v_pk_fma_f32 v[26:27], v[12:13], v[36:37], v[26:27] op_sel:[0,1,0] op_sel_hi:[1,1,1]
	v_pk_fma_f32 v[14:15], v[14:15], v[40:41], v[18:19] op_sel_hi:[1,0,1]
	v_pk_fma_f32 v[16:17], v[16:17], v[40:41], v[20:21] op_sel_hi:[1,0,1]
	v_add_f32_dpp v26, v26, v26 row_ror:8 row_mask:0xf bank_mask:0x3 bound_ctrl:1
	v_add_f32_dpp v26, v27, v27 row_ror:8 row_mask:0xf bank_mask:0xc bound_ctrl:1
	ds_read_b128 v[54:57], v1 offset:31248
	ds_read_b128 v[44:47], v2 offset:25344
	v_add_f32_dpp v26, v26, v26 row_half_mirror row_mask:0xf bank_mask:0xf bound_ctrl:1
	ds_read_b64 v[52:53], v3 offset:29184
	ds_read_b128 v[48:51], v2 offset:25600
	v_add_f32_dpp v26, v26, v26 quad_perm:[1,0,3,2] row_mask:0xf bank_mask:0xf bound_ctrl:1
	s_add_u32 s14, s14, 0x1000
	s_addc_u32 s15, s15, 0
	v_add_f32_dpp v26, v26, v26 quad_perm:[2,3,0,1] row_mask:0xf bank_mask:0xf bound_ctrl:1
	s_cmp_eq_u32 s21, 0
	s_cbranch_scc1 .Lml2_den1_0
.Lml2_back1_0:
	v_mov_b32_dpp v27, v26 row_ror:8 row_mask:0xf bank_mask:0xf bound_ctrl:1
	s_mov_b64 exec, s[18:19]
	v_cvt_pk_bf16_f32 v28, v26, v27
	global_store_dword v4, v28, s[14:15] offset:-4096
	s_mov_b64 exec, -1
	s_waitcnt lgkmcnt(2)
	v_pk_mul_f32 v[18:19], v[44:45], v[54:55] op_sel:[0,1] op_sel_hi:[1,1]
	v_pk_mul_f32 v[20:21], v[46:47], v[54:55] op_sel:[0,1] op_sel_hi:[1,1]
	s_waitcnt lgkmcnt(1)
	v_pk_mul_f32 v[22:23], v[52:53], v[18:19] op_sel:[0,0] op_sel_hi:[1,0]
	v_pk_fma_f32 v[6:7], v[6:7], v[54:55], v[22:23] op_sel_hi:[1,0,1]
	s_waitcnt lgkmcnt(0)
	v_pk_mul_f32 v[26:27], v[6:7], v[48:49] op_sel_hi:[1,0]
	v_pk_mul_f32 v[24:25], v[52:53], v[18:19] op_sel:[0,1] op_sel_hi:[1,1]
	v_pk_fma_f32 v[8:9], v[8:9], v[54:55], v[24:25] op_sel_hi:[1,0,1]
	v_pk_fma_f32 v[26:27], v[8:9], v[48:49], v[26:27] op_sel:[0,1,0] op_sel_hi:[1,1,1]
	v_pk_mul_f32 v[22:23], v[52:53], v[20:21] op_sel:[0,0] op_sel_hi:[1,0]
	v_pk_fma_f32 v[10:11], v[10:11], v[54:55], v[22:23] op_sel_hi:[1,0,1]
	v_pk_fma_f32 v[26:27], v[10:11], v[50:51], v[26:27] op_sel:[0,0,0] op_sel_hi:[1,0,1]
	v_pk_mul_f32 v[24:25], v[52:53], v[20:21] op_sel:[0,1] op_sel_hi:[1,1]
	v_pk_fma_f32 v[12:13], v[12:13], v[54:55], v[24:25] op_sel_hi:[1,0,1]
	v_pk_fma_f32 v[26:27], v[12:13], v[50:51], v[26:27] op_sel:[0,1,0] op_sel_hi:[1,1,1]
	v_pk_fma_f32 v[14:15], v[14:15], v[54:55], v[18:19] op_sel_hi:[1,0,1]
	v_pk_fma_f32 v[16:17], v[16:17], v[54:55], v[20:21] op_sel_hi:[1,0,1]
	v_add_f32_dpp v26, v26, v26 row_ror:8 row_mask:0xf bank_mask:0x3 bound_ctrl:1
	v_add_f32_dpp v26, v27, v27 row_ror:8 row_mask:0xf bank_mask:0xc bound_ctrl:1
	ds_read_b128 v[40:43], v1 offset:31264
	ds_read_b128 v[30:33], v2 offset:25856
	v_add_f32_dpp v26, v26, v26 row_half_mirror row_mask:0xf bank_mask:0xf bound_ctrl:1
	ds_read_b64 v[38:39], v3 offset:29440
	ds_read_b128 v[34:37], v2 offset:26112
	v_add_f32_dpp v26, v26, v26 quad_perm:[1,0,3,2] row_mask:0xf bank_mask:0xf bound_ctrl:1
	s_add_u32 s14, s14, 0x1000
	s_addc_u32 s15, s15, 0
	v_add_f32_dpp v26, v26, v26 quad_perm:[2,3,0,1] row_mask:0xf bank_mask:0xf bound_ctrl:1
	s_cmp_eq_u32 s21, 1
	s_cbranch_scc1 .Lml2_den1_1
.Lml2_back1_1:
	v_mov_b32_dpp v27, v26 row_ror:8 row_mask:0xf bank_mask:0xf bound_ctrl:1
	s_mov_b64 exec, s[18:19]
	v_cvt_pk_bf16_f32 v28, v26, v27
	global_store_dword v4, v28, s[14:15] offset:-4096
	s_mov_b64 exec, -1
	s_waitcnt lgkmcnt(2)
	v_pk_mul_f32 v[18:19], v[30:31], v[40:41] op_sel:[0,1] op_sel_hi:[1,1]
	v_pk_mul_f32 v[20:21], v[32:33], v[40:41] op_sel:[0,1] op_sel_hi:[1,1]
	s_waitcnt lgkmcnt(1)
	v_pk_mul_f32 v[22:23], v[38:39], v[18:19] op_sel:[0,0] op_sel_hi:[1,0]
	v_pk_fma_f32 v[6:7], v[6:7], v[40:41], v[22:23] op_sel_hi:[1,0,1]
	s_waitcnt lgkmcnt(0)
	v_pk_mul_f32 v[26:27], v[6:7], v[34:35] op_sel_hi:[1,0]
	v_pk_mul_f32 v[24:25], v[38:39], v[18:19] op_sel:[0,1] op_sel_hi:[1,1]
	v_pk_fma_f32 v[8:9], v[8:9], v[40:41], v[24:25] op_sel_hi:[1,0,1]
	v_pk_fma_f32 v[26:27], v[8:9], v[34:35], v[26:27] op_sel:[0,1,0] op_sel_hi:[1,1,1]
	v_pk_mul_f32 v[22:23], v[38:39], v[20:21] op_sel:[0,0] op_sel_hi:[1,0]
	v_pk_fma_f32 v[10:11], v[10:11], v[40:41], v[22:23] op_sel_hi:[1,0,1]
	v_pk_fma_f32 v[26:27], v[10:11], v[36:37], v[26:27] op_sel:[0,0,0] op_sel_hi:[1,0,1]
	v_pk_mul_f32 v[24:25], v[38:39], v[20:21] op_sel:[0,1] op_sel_hi:[1,1]
	v_pk_fma_f32 v[12:13], v[12:13], v[40:41], v[24:25] op_sel_hi:[1,0,1]
	v_pk_fma_f32 v[26:27], v[12:13], v[36:37], v[26:27] op_sel:[0,1,0] op_sel_hi:[1,1,1]
	v_pk_fma_f32 v[14:15], v[14:15], v[40:41], v[18:19] op_sel_hi:[1,0,1]
	v_pk_fma_f32 v[16:17], v[16:17], v[40:41], v[20:21] op_sel_hi:[1,0,1]
	v_add_f32_dpp v26, v26, v26 row_ror:8 row_mask:0xf bank_mask:0x3 bound_ctrl:1
	v_add_f32_dpp v26, v27, v27 row_ror:8 row_mask:0xf bank_mask:0xc bound_ctrl:1
	ds_read_b128 v[54:57], v1 offset:31280
	ds_read_b128 v[44:47], v2 offset:26368
	v_add_f32_dpp v26, v26, v26 row_half_mirror row_mask:0xf bank_mask:0xf bound_ctrl:1
	ds_read_b64 v[52:53], v3 offset:29696
	ds_read_b128 v[48:51], v2 offset:26624
	v_add_f32_dpp v26, v26, v26 quad_perm:[1,0,3,2] row_mask:0xf bank_mask:0xf bound_ctrl:1
	s_add_u32 s14, s14, 0x1000
	s_addc_u32 s15, s15, 0
	v_add_f32_dpp v26, v26, v26 quad_perm:[2,3,0,1] row_mask:0xf bank_mask:0xf bound_ctrl:1
	s_cmp_eq_u32 s21, 2
	s_cbranch_scc1 .Lml2_den1_2
.Lml2_back1_2:
	v_mov_b32_dpp v27, v26 row_ror:8 row_mask:0xf bank_mask:0xf bound_ctrl:1
	s_mov_b64 exec, s[18:19]
	v_cvt_pk_bf16_f32 v28, v26, v27
	global_store_dword v4, v28, s[14:15] offset:-4096
	s_mov_b64 exec, -1
	s_waitcnt lgkmcnt(2)
	v_pk_mul_f32 v[18:19], v[44:45], v[54:55] op_sel:[0,1] op_sel_hi:[1,1]
	v_pk_mul_f32 v[20:21], v[46:47], v[54:55] op_sel:[0,1] op_sel_hi:[1,1]
	s_waitcnt lgkmcnt(1)
	v_pk_mul_f32 v[22:23], v[52:53], v[18:19] op_sel:[0,0] op_sel_hi:[1,0]
	v_pk_fma_f32 v[6:7], v[6:7], v[54:55], v[22:23] op_sel_hi:[1,0,1]
	s_waitcnt lgkmcnt(0)
	v_pk_mul_f32 v[26:27], v[6:7], v[48:49] op_sel_hi:[1,0]
	v_pk_mul_f32 v[24:25], v[52:53], v[18:19] op_sel:[0,1] op_sel_hi:[1,1]
	v_pk_fma_f32 v[8:9], v[8:9], v[54:55], v[24:25] op_sel_hi:[1,0,1]
	v_pk_fma_f32 v[26:27], v[8:9], v[48:49], v[26:27] op_sel:[0,1,0] op_sel_hi:[1,1,1]
	v_pk_mul_f32 v[22:23], v[52:53], v[20:21] op_sel:[0,0] op_sel_hi:[1,0]
	v_pk_fma_f32 v[10:11], v[10:11], v[54:55], v[22:23] op_sel_hi:[1,0,1]
	v_pk_fma_f32 v[26:27], v[10:11], v[50:51], v[26:27] op_sel:[0,0,0] op_sel_hi:[1,0,1]
	v_pk_mul_f32 v[24:25], v[52:53], v[20:21] op_sel:[0,1] op_sel_hi:[1,1]
	v_pk_fma_f32 v[12:13], v[12:13], v[54:55], v[24:25] op_sel_hi:[1,0,1]
	v_pk_fma_f32 v[26:27], v[12:13], v[50:51], v[26:27] op_sel:[0,1,0] op_sel_hi:[1,1,1]
	v_pk_fma_f32 v[14:15], v[14:15], v[54:55], v[18:19] op_sel_hi:[1,0,1]
	v_pk_fma_f32 v[16:17], v[16:17], v[54:55], v[20:21] op_sel_hi:[1,0,1]
	v_add_f32_dpp v26, v26, v26 row_ror:8 row_mask:0xf bank_mask:0x3 bound_ctrl:1
	v_add_f32_dpp v26, v27, v27 row_ror:8 row_mask:0xf bank_mask:0xc bound_ctrl:1
	ds_read_b128 v[40:43], v1 offset:31296
	ds_read_b128 v[30:33], v2 offset:26880
	v_add_f32_dpp v26, v26, v26 row_half_mirror row_mask:0xf bank_mask:0xf bound_ctrl:1
	ds_read_b64 v[38:39], v3 offset:29952
	ds_read_b128 v[34:37], v2 offset:27136
	v_add_f32_dpp v26, v26, v26 quad_perm:[1,0,3,2] row_mask:0xf bank_mask:0xf bound_ctrl:1
	s_add_u32 s14, s14, 0x1000
	s_addc_u32 s15, s15, 0
	v_add_f32_dpp v26, v26, v26 quad_perm:[2,3,0,1] row_mask:0xf bank_mask:0xf bound_ctrl:1
	s_cmp_eq_u32 s21, 3
	s_cbranch_scc1 .Lml2_den1_3
.Lml2_back1_3:
	v_mov_b32_dpp v27, v26 row_ror:8 row_mask:0xf bank_mask:0xf bound_ctrl:1
	s_mov_b64 exec, s[18:19]
	v_cvt_pk_bf16_f32 v28, v26, v27
	global_store_dword v4, v28, s[14:15] offset:-4096
	s_mov_b64 exec, -1
	s_waitcnt lgkmcnt(2)
	v_pk_mul_f32 v[18:19], v[30:31], v[40:41] op_sel:[0,1] op_sel_hi:[1,1]
	v_pk_mul_f32 v[20:21], v[32:33], v[40:41] op_sel:[0,1] op_sel_hi:[1,1]
	s_waitcnt lgkmcnt(1)
	v_pk_mul_f32 v[22:23], v[38:39], v[18:19] op_sel:[0,0] op_sel_hi:[1,0]
	v_pk_fma_f32 v[6:7], v[6:7], v[40:41], v[22:23] op_sel_hi:[1,0,1]
	s_waitcnt lgkmcnt(0)
	v_pk_mul_f32 v[26:27], v[6:7], v[34:35] op_sel_hi:[1,0]
	v_pk_mul_f32 v[24:25], v[38:39], v[18:19] op_sel:[0,1] op_sel_hi:[1,1]
	v_pk_fma_f32 v[8:9], v[8:9], v[40:41], v[24:25] op_sel_hi:[1,0,1]
	v_pk_fma_f32 v[26:27], v[8:9], v[34:35], v[26:27] op_sel:[0,1,0] op_sel_hi:[1,1,1]
	v_pk_mul_f32 v[22:23], v[38:39], v[20:21] op_sel:[0,0] op_sel_hi:[1,0]
	v_pk_fma_f32 v[10:11], v[10:11], v[40:41], v[22:23] op_sel_hi:[1,0,1]
	v_pk_fma_f32 v[26:27], v[10:11], v[36:37], v[26:27] op_sel:[0,0,0] op_sel_hi:[1,0,1]
	v_pk_mul_f32 v[24:25], v[38:39], v[20:21] op_sel:[0,1] op_sel_hi:[1,1]
	v_pk_fma_f32 v[12:13], v[12:13], v[40:41], v[24:25] op_sel_hi:[1,0,1]
	v_pk_fma_f32 v[26:27], v[12:13], v[36:37], v[26:27] op_sel:[0,1,0] op_sel_hi:[1,1,1]
	v_pk_fma_f32 v[14:15], v[14:15], v[40:41], v[18:19] op_sel_hi:[1,0,1]
	v_pk_fma_f32 v[16:17], v[16:17], v[40:41], v[20:21] op_sel_hi:[1,0,1]
	v_add_f32_dpp v26, v26, v26 row_ror:8 row_mask:0xf bank_mask:0x3 bound_ctrl:1
	v_add_f32_dpp v26, v27, v27 row_ror:8 row_mask:0xf bank_mask:0xc bound_ctrl:1
	ds_read_b128 v[54:57], v1 offset:31312
	ds_read_b128 v[44:47], v2 offset:27392
	v_add_f32_dpp v26, v26, v26 row_half_mirror row_mask:0xf bank_mask:0xf bound_ctrl:1
	ds_read_b64 v[52:53], v3 offset:30208
	ds_read_b128 v[48:51], v2 offset:27648
	v_add_f32_dpp v26, v26, v26 quad_perm:[1,0,3,2] row_mask:0xf bank_mask:0xf bound_ctrl:1
	s_add_u32 s14, s14, 0x1000
	s_addc_u32 s15, s15, 0
	v_add_f32_dpp v26, v26, v26 quad_perm:[2,3,0,1] row_mask:0xf bank_mask:0xf bound_ctrl:1
	s_cmp_eq_u32 s21, 4
	s_cbranch_scc1 .Lml2_den1_4
.Lml2_back1_4:
	v_mov_b32_dpp v27, v26 row_ror:8 row_mask:0xf bank_mask:0xf bound_ctrl:1
	s_mov_b64 exec, s[18:19]
	v_cvt_pk_bf16_f32 v28, v26, v27
	global_store_dword v4, v28, s[14:15] offset:-4096
	s_mov_b64 exec, -1
	s_waitcnt lgkmcnt(2)
	v_pk_mul_f32 v[18:19], v[44:45], v[54:55] op_sel:[0,1] op_sel_hi:[1,1]
	v_pk_mul_f32 v[20:21], v[46:47], v[54:55] op_sel:[0,1] op_sel_hi:[1,1]
	s_waitcnt lgkmcnt(1)
	v_pk_mul_f32 v[22:23], v[52:53], v[18:19] op_sel:[0,0] op_sel_hi:[1,0]
	v_pk_fma_f32 v[6:7], v[6:7], v[54:55], v[22:23] op_sel_hi:[1,0,1]
	s_waitcnt lgkmcnt(0)
	v_pk_mul_f32 v[26:27], v[6:7], v[48:49] op_sel_hi:[1,0]
	v_pk_mul_f32 v[24:25], v[52:53], v[18:19] op_sel:[0,1] op_sel_hi:[1,1]
	v_pk_fma_f32 v[8:9], v[8:9], v[54:55], v[24:25] op_sel_hi:[1,0,1]
	v_pk_fma_f32 v[26:27], v[8:9], v[48:49], v[26:27] op_sel:[0,1,0] op_sel_hi:[1,1,1]
	v_pk_mul_f32 v[22:23], v[52:53], v[20:21] op_sel:[0,0] op_sel_hi:[1,0]
	v_pk_fma_f32 v[10:11], v[10:11], v[54:55], v[22:23] op_sel_hi:[1,0,1]
	v_pk_fma_f32 v[26:27], v[10:11], v[50:51], v[26:27] op_sel:[0,0,0] op_sel_hi:[1,0,1]
	v_pk_mul_f32 v[24:25], v[52:53], v[20:21] op_sel:[0,1] op_sel_hi:[1,1]
	v_pk_fma_f32 v[12:13], v[12:13], v[54:55], v[24:25] op_sel_hi:[1,0,1]
	v_pk_fma_f32 v[26:27], v[12:13], v[50:51], v[26:27] op_sel:[0,1,0] op_sel_hi:[1,1,1]
	v_pk_fma_f32 v[14:15], v[14:15], v[54:55], v[18:19] op_sel_hi:[1,0,1]
	v_pk_fma_f32 v[16:17], v[16:17], v[54:55], v[20:21] op_sel_hi:[1,0,1]
	v_add_f32_dpp v26, v26, v26 row_ror:8 row_mask:0xf bank_mask:0x3 bound_ctrl:1
	v_add_f32_dpp v26, v27, v27 row_ror:8 row_mask:0xf bank_mask:0xc bound_ctrl:1
	ds_read_b128 v[40:43], v1 offset:31328
	ds_read_b128 v[30:33], v2 offset:27904
	v_add_f32_dpp v26, v26, v26 row_half_mirror row_mask:0xf bank_mask:0xf bound_ctrl:1
	ds_read_b64 v[38:39], v3 offset:30464
	ds_read_b128 v[34:37], v2 offset:28160
	v_add_f32_dpp v26, v26, v26 quad_perm:[1,0,3,2] row_mask:0xf bank_mask:0xf bound_ctrl:1
	s_add_u32 s14, s14, 0x1000
	s_addc_u32 s15, s15, 0
	v_add_f32_dpp v26, v26, v26 quad_perm:[2,3,0,1] row_mask:0xf bank_mask:0xf bound_ctrl:1
	s_cmp_eq_u32 s21, 5
	s_cbranch_scc1 .Lml2_den1_5
.Lml2_back1_5:
	v_mov_b32_dpp v27, v26 row_ror:8 row_mask:0xf bank_mask:0xf bound_ctrl:1
	s_mov_b64 exec, s[18:19]
	v_cvt_pk_bf16_f32 v28, v26, v27
	global_store_dword v4, v28, s[14:15] offset:-4096
	s_mov_b64 exec, -1
	s_waitcnt lgkmcnt(2)
	v_pk_mul_f32 v[18:19], v[30:31], v[40:41] op_sel:[0,1] op_sel_hi:[1,1]
	v_pk_mul_f32 v[20:21], v[32:33], v[40:41] op_sel:[0,1] op_sel_hi:[1,1]
	s_waitcnt lgkmcnt(1)
	v_pk_mul_f32 v[22:23], v[38:39], v[18:19] op_sel:[0,0] op_sel_hi:[1,0]
	v_pk_fma_f32 v[6:7], v[6:7], v[40:41], v[22:23] op_sel_hi:[1,0,1]
	s_waitcnt lgkmcnt(0)
	v_pk_mul_f32 v[26:27], v[6:7], v[34:35] op_sel_hi:[1,0]
	v_pk_mul_f32 v[24:25], v[38:39], v[18:19] op_sel:[0,1] op_sel_hi:[1,1]
	v_pk_fma_f32 v[8:9], v[8:9], v[40:41], v[24:25] op_sel_hi:[1,0,1]
	v_pk_fma_f32 v[26:27], v[8:9], v[34:35], v[26:27] op_sel:[0,1,0] op_sel_hi:[1,1,1]
	v_pk_mul_f32 v[22:23], v[38:39], v[20:21] op_sel:[0,0] op_sel_hi:[1,0]
	v_pk_fma_f32 v[10:11], v[10:11], v[40:41], v[22:23] op_sel_hi:[1,0,1]
	v_pk_fma_f32 v[26:27], v[10:11], v[36:37], v[26:27] op_sel:[0,0,0] op_sel_hi:[1,0,1]
	v_pk_mul_f32 v[24:25], v[38:39], v[20:21] op_sel:[0,1] op_sel_hi:[1,1]
	v_pk_fma_f32 v[12:13], v[12:13], v[40:41], v[24:25] op_sel_hi:[1,0,1]
	v_pk_fma_f32 v[26:27], v[12:13], v[36:37], v[26:27] op_sel:[0,1,0] op_sel_hi:[1,1,1]
	v_pk_fma_f32 v[14:15], v[14:15], v[40:41], v[18:19] op_sel_hi:[1,0,1]
	v_pk_fma_f32 v[16:17], v[16:17], v[40:41], v[20:21] op_sel_hi:[1,0,1]
	v_add_f32_dpp v26, v26, v26 row_ror:8 row_mask:0xf bank_mask:0x3 bound_ctrl:1
	v_add_f32_dpp v26, v27, v27 row_ror:8 row_mask:0xf bank_mask:0xc bound_ctrl:1
	ds_read_b128 v[54:57], v1 offset:31344
	ds_read_b128 v[44:47], v2 offset:28416
	v_add_f32_dpp v26, v26, v26 row_half_mirror row_mask:0xf bank_mask:0xf bound_ctrl:1
	ds_read_b64 v[52:53], v3 offset:30720
	ds_read_b128 v[48:51], v2 offset:28672
	v_add_f32_dpp v26, v26, v26 quad_perm:[1,0,3,2] row_mask:0xf bank_mask:0xf bound_ctrl:1
	s_add_u32 s14, s14, 0x1000
	s_addc_u32 s15, s15, 0
	v_add_f32_dpp v26, v26, v26 quad_perm:[2,3,0,1] row_mask:0xf bank_mask:0xf bound_ctrl:1
	s_cmp_eq_u32 s21, 6
	s_cbranch_scc1 .Lml2_den1_6
.Lml2_back1_6:
	v_mov_b32_dpp v27, v26 row_ror:8 row_mask:0xf bank_mask:0xf bound_ctrl:1
	s_mov_b64 exec, s[18:19]
	v_cvt_pk_bf16_f32 v28, v26, v27
	global_store_dword v4, v28, s[14:15] offset:-4096
	s_mov_b64 exec, -1
	s_waitcnt lgkmcnt(2)
	v_pk_mul_f32 v[18:19], v[44:45], v[54:55] op_sel:[0,1] op_sel_hi:[1,1]
	v_pk_mul_f32 v[20:21], v[46:47], v[54:55] op_sel:[0,1] op_sel_hi:[1,1]
	s_waitcnt lgkmcnt(1)
	v_pk_mul_f32 v[22:23], v[52:53], v[18:19] op_sel:[0,0] op_sel_hi:[1,0]
	v_pk_fma_f32 v[6:7], v[6:7], v[54:55], v[22:23] op_sel_hi:[1,0,1]
	s_waitcnt lgkmcnt(0)
	v_pk_mul_f32 v[26:27], v[6:7], v[48:49] op_sel_hi:[1,0]
	v_pk_mul_f32 v[24:25], v[52:53], v[18:19] op_sel:[0,1] op_sel_hi:[1,1]
	v_pk_fma_f32 v[8:9], v[8:9], v[54:55], v[24:25] op_sel_hi:[1,0,1]
	v_pk_fma_f32 v[26:27], v[8:9], v[48:49], v[26:27] op_sel:[0,1,0] op_sel_hi:[1,1,1]
	v_pk_mul_f32 v[22:23], v[52:53], v[20:21] op_sel:[0,0] op_sel_hi:[1,0]
	v_pk_fma_f32 v[10:11], v[10:11], v[54:55], v[22:23] op_sel_hi:[1,0,1]
	v_pk_fma_f32 v[26:27], v[10:11], v[50:51], v[26:27] op_sel:[0,0,0] op_sel_hi:[1,0,1]
	v_pk_mul_f32 v[24:25], v[52:53], v[20:21] op_sel:[0,1] op_sel_hi:[1,1]
	v_pk_fma_f32 v[12:13], v[12:13], v[54:55], v[24:25] op_sel_hi:[1,0,1]
	v_pk_fma_f32 v[26:27], v[12:13], v[50:51], v[26:27] op_sel:[0,1,0] op_sel_hi:[1,1,1]
	v_pk_fma_f32 v[14:15], v[14:15], v[54:55], v[18:19] op_sel_hi:[1,0,1]
	v_pk_fma_f32 v[16:17], v[16:17], v[54:55], v[20:21] op_sel_hi:[1,0,1]
	v_add_f32_dpp v26, v26, v26 row_ror:8 row_mask:0xf bank_mask:0x3 bound_ctrl:1
	v_add_f32_dpp v26, v27, v27 row_ror:8 row_mask:0xf bank_mask:0xc bound_ctrl:1
	ds_read_b128 v[40:43], v1 offset:47616
	ds_read_b128 v[30:33], v2 offset:41216
	v_add_f32_dpp v26, v26, v26 row_half_mirror row_mask:0xf bank_mask:0xf bound_ctrl:1
	ds_read_b64 v[38:39], v3 offset:45312
	ds_read_b128 v[34:37], v2 offset:41472
	v_add_f32_dpp v26, v26, v26 quad_perm:[1,0,3,2] row_mask:0xf bank_mask:0xf bound_ctrl:1
	s_add_u32 s14, s14, 0x1000
	s_addc_u32 s15, s15, 0
	v_add_f32_dpp v26, v26, v26 quad_perm:[2,3,0,1] row_mask:0xf bank_mask:0xf bound_ctrl:1
	s_cmp_eq_u32 s21, 7
	s_cbranch_scc1 .Lml2_den1_7
.Lml2_back1_7:
	v_mov_b32_dpp v27, v26 row_ror:8 row_mask:0xf bank_mask:0xf bound_ctrl:1
	s_mov_b64 exec, s[18:19]
	v_cvt_pk_bf16_f32 v28, v26, v27
	global_store_dword v4, v28, s[14:15] offset:-4096
	s_mov_b64 exec, -1
	s_waitcnt vmcnt(8)
	v_lshlrev_b32_e32 v88, 16, v80
	v_lshlrev_b32_e32 v89, 16, v81
	v_and_b32_e32 v90, s17, v80
	v_and_b32_e32 v91, s17, v81
	v_lshlrev_b32_e32 v92, 16, v82
	v_and_b32_e32 v93, s17, v82
	v_lshlrev_b32_e32 v94, 16, v83
	v_and_b32_e32 v95, s17, v83
	v_lshlrev_b32_e32 v96, 16, v84
	v_and_b32_e32 v97, s17, v84
	ds_write_b128 v69, v[88:91] offset:256
	ds_write_b64 v70, v[92:93] offset:256
	ds_write_b64 v71, v[94:95] offset:256
	ds_write_b64 v71, v[96:97] offset:384
	ds_write_b32 v72, v85 offset:256
	s_cmp_lg_u32 s36, 4
	s_cbranch_scc1 .Lml2_nsc3
	v_mov_b32_e32 v98, v87
	s_nop 1
	v_add_f32_dpp v98, v98, v98 row_shr:1 row_mask:0xf bank_mask:0xf bound_ctrl:1
	s_nop 1
	v_add_f32_dpp v98, v98, v98 row_shr:2 row_mask:0xf bank_mask:0xf bound_ctrl:1
	s_nop 1
	v_add_f32_dpp v98, v98, v98 row_shr:4 row_mask:0xf bank_mask:0xf bound_ctrl:1
	s_nop 1
	v_sub_f32_e32 v99, v86, v98
	s_nop 1
	v_max_f32_dpp v99, v99, v99 row_shr:1 row_mask:0xf bank_mask:0xf
	s_nop 1
	v_max_f32_dpp v99, v99, v99 row_shr:2 row_mask:0xf bank_mask:0xf
	s_nop 1
	v_max_f32_dpp v99, v99, v99 row_shr:4 row_mask:0xf bank_mask:0xf
	s_nop 1
	v_max_f32_e32 v99, v99, v0
	v_add_f32_e32 v103, v98, v99
	v_mov_b32_e32 v105, v0
	s_nop 1
	v_mov_b32_dpp v105, v103 row_shr:1 row_mask:0xf bank_mask:0xf
	v_sub_f32_e32 v104, v86, v103
	v_add_f32_e32 v105, v87, v105
	v_fma_f32 v104, v104, s29, v29
	v_sub_f32_e32 v105, v105, v103
	v_exp_f32_e32 v101, v104
	v_mul_f32_e32 v105, s29, v105
	v_mul_f32_e32 v104, 0xbfb8aa3b, v103
	v_exp_f32_e32 v100, v105
	v_exp_f32_e32 v102, v104
	v_readlane_b32 s4, v103, 7
	s_nop 3
	v_mov_b32_e32 v0, s4
	ds_write_b128 v73, v[100:103] offset:256

.Lml2_nsl4:
	s_add_u32 s22, s22, 0x400
	s_addc_u32 s23, s23, 0
	s_add_u32 s8, s8, 0xc000
	s_addc_u32 s9, s9, 0
	s_add_u32 s10, s10, 0x20000
	s_addc_u32 s11, s11, 0
	s_add_u32 s12, s12, 0x400
	s_addc_u32 s13, s13, 0
	s_waitcnt lgkmcnt(2)
	v_pk_mul_f32 v[18:19], v[30:31], v[40:41] op_sel:[0,1] op_sel_hi:[1,1]
	v_pk_mul_f32 v[20:21], v[32:33], v[40:41] op_sel:[0,1] op_sel_hi:[1,1]
	s_waitcnt lgkmcnt(1)
	v_pk_mul_f32 v[22:23], v[38:39], v[18:19] op_sel:[0,0] op_sel_hi:[1,0]
	v_pk_fma_f32 v[6:7], v[6:7], v[40:41], v[22:23] op_sel_hi:[1,0,1]
	s_waitcnt lgkmcnt(0)
	v_pk_mul_f32 v[26:27], v[6:7], v[34:35] op_sel_hi:[1,0]
	v_pk_mul_f32 v[24:25], v[38:39], v[18:19] op_sel:[0,1] op_sel_hi:[1,1]
	v_pk_fma_f32 v[8:9], v[8:9], v[40:41], v[24:25] op_sel_hi:[1,0,1]
	v_pk_fma_f32 v[26:27], v[8:9], v[34:35], v[26:27] op_sel:[0,1,0] op_sel_hi:[1,1,1]
	v_pk_mul_f32 v[22:23], v[38:39], v[20:21] op_sel:[0,0] op_sel_hi:[1,0]
	v_pk_fma_f32 v[10:11], v[10:11], v[40:41], v[22:23] op_sel_hi:[1,0,1]
	v_pk_fma_f32 v[26:27], v[10:11], v[36:37], v[26:27] op_sel:[0,0,0] op_sel_hi:[1,0,1]
	v_pk_mul_f32 v[24:25], v[38:39], v[20:21] op_sel:[0,1] op_sel_hi:[1,1]
	v_pk_fma_f32 v[12:13], v[12:13], v[40:41], v[24:25] op_sel_hi:[1,0,1]
	v_pk_fma_f32 v[26:27], v[12:13], v[36:37], v[26:27] op_sel:[0,1,0] op_sel_hi:[1,1,1]
	v_pk_fma_f32 v[14:15], v[14:15], v[40:41], v[18:19] op_sel_hi:[1,0,1]
	v_pk_fma_f32 v[16:17], v[16:17], v[40:41], v[20:21] op_sel_hi:[1,0,1]
	v_add_f32_dpp v26, v26, v26 row_ror:8 row_mask:0xf bank_mask:0x3 bound_ctrl:1
	v_add_f32_dpp v26, v27, v27 row_ror:8 row_mask:0xf bank_mask:0xc bound_ctrl:1
	ds_read_b128 v[54:57], v1 offset:47632
	ds_read_b128 v[44:47], v2 offset:41728
	v_add_f32_dpp v26, v26, v26 row_half_mirror row_mask:0xf bank_mask:0xf bound_ctrl:1
	ds_read_b64 v[52:53], v3 offset:45568
	ds_read_b128 v[48:51], v2 offset:41984
	v_add_f32_dpp v26, v26, v26 quad_perm:[1,0,3,2] row_mask:0xf bank_mask:0xf bound_ctrl:1
	s_add_u32 s14, s14, 0x1000
	s_addc_u32 s15, s15, 0
	v_add_f32_dpp v26, v26, v26 quad_perm:[2,3,0,1] row_mask:0xf bank_mask:0xf bound_ctrl:1
	s_cmp_eq_u32 s21, 0
	s_cbranch_scc1 .Lml2_den2_0
.Lml2_back2_0:
	v_mov_b32_dpp v27, v26 row_ror:8 row_mask:0xf bank_mask:0xf bound_ctrl:1
	s_mov_b64 exec, s[18:19]
	v_cvt_pk_bf16_f32 v28, v26, v27
	global_store_dword v4, v28, s[14:15] offset:-4096
	s_mov_b64 exec, -1
	s_waitcnt lgkmcnt(2)
	v_pk_mul_f32 v[18:19], v[44:45], v[54:55] op_sel:[0,1] op_sel_hi:[1,1]
	v_pk_mul_f32 v[20:21], v[46:47], v[54:55] op_sel:[0,1] op_sel_hi:[1,1]
	s_waitcnt lgkmcnt(1)
	v_pk_mul_f32 v[22:23], v[52:53], v[18:19] op_sel:[0,0] op_sel_hi:[1,0]
	v_pk_fma_f32 v[6:7], v[6:7], v[54:55], v[22:23] op_sel_hi:[1,0,1]
	s_waitcnt lgkmcnt(0)
	v_pk_mul_f32 v[26:27], v[6:7], v[48:49] op_sel_hi:[1,0]
	v_pk_mul_f32 v[24:25], v[52:53], v[18:19] op_sel:[0,1] op_sel_hi:[1,1]
	v_pk_fma_f32 v[8:9], v[8:9], v[54:55], v[24:25] op_sel_hi:[1,0,1]
	v_pk_fma_f32 v[26:27], v[8:9], v[48:49], v[26:27] op_sel:[0,1,0] op_sel_hi:[1,1,1]
	v_pk_mul_f32 v[22:23], v[52:53], v[20:21] op_sel:[0,0] op_sel_hi:[1,0]
	v_pk_fma_f32 v[10:11], v[10:11], v[54:55], v[22:23] op_sel_hi:[1,0,1]
	v_pk_fma_f32 v[26:27], v[10:11], v[50:51], v[26:27] op_sel:[0,0,0] op_sel_hi:[1,0,1]
	v_pk_mul_f32 v[24:25], v[52:53], v[20:21] op_sel:[0,1] op_sel_hi:[1,1]
	v_pk_fma_f32 v[12:13], v[12:13], v[54:55], v[24:25] op_sel_hi:[1,0,1]
	v_pk_fma_f32 v[26:27], v[12:13], v[50:51], v[26:27] op_sel:[0,1,0] op_sel_hi:[1,1,1]
	v_pk_fma_f32 v[14:15], v[14:15], v[54:55], v[18:19] op_sel_hi:[1,0,1]
	v_pk_fma_f32 v[16:17], v[16:17], v[54:55], v[20:21] op_sel_hi:[1,0,1]
	v_add_f32_dpp v26, v26, v26 row_ror:8 row_mask:0xf bank_mask:0x3 bound_ctrl:1
	v_add_f32_dpp v26, v27, v27 row_ror:8 row_mask:0xf bank_mask:0xc bound_ctrl:1
	ds_read_b128 v[40:43], v1 offset:47648
	ds_read_b128 v[30:33], v2 offset:42240
	v_add_f32_dpp v26, v26, v26 row_half_mirror row_mask:0xf bank_mask:0xf bound_ctrl:1
	ds_read_b64 v[38:39], v3 offset:45824
	ds_read_b128 v[34:37], v2 offset:42496
	v_add_f32_dpp v26, v26, v26 quad_perm:[1,0,3,2] row_mask:0xf bank_mask:0xf bound_ctrl:1
	s_add_u32 s14, s14, 0x1000
	s_addc_u32 s15, s15, 0
	v_add_f32_dpp v26, v26, v26 quad_perm:[2,3,0,1] row_mask:0xf bank_mask:0xf bound_ctrl:1
	s_cmp_eq_u32 s21, 1
	s_cbranch_scc1 .Lml2_den2_1
.Lml2_back2_1:
	v_mov_b32_dpp v27, v26 row_ror:8 row_mask:0xf bank_mask:0xf bound_ctrl:1
	s_mov_b64 exec, s[18:19]
	v_cvt_pk_bf16_f32 v28, v26, v27
	global_store_dword v4, v28, s[14:15] offset:-4096
	s_mov_b64 exec, -1
	s_waitcnt lgkmcnt(2)
	v_pk_mul_f32 v[18:19], v[30:31], v[40:41] op_sel:[0,1] op_sel_hi:[1,1]
	v_pk_mul_f32 v[20:21], v[32:33], v[40:41] op_sel:[0,1] op_sel_hi:[1,1]
	s_waitcnt lgkmcnt(1)
	v_pk_mul_f32 v[22:23], v[38:39], v[18:19] op_sel:[0,0] op_sel_hi:[1,0]
	v_pk_fma_f32 v[6:7], v[6:7], v[40:41], v[22:23] op_sel_hi:[1,0,1]
	s_waitcnt lgkmcnt(0)
	v_pk_mul_f32 v[26:27], v[6:7], v[34:35] op_sel_hi:[1,0]
	v_pk_mul_f32 v[24:25], v[38:39], v[18:19] op_sel:[0,1] op_sel_hi:[1,1]
	v_pk_fma_f32 v[8:9], v[8:9], v[40:41], v[24:25] op_sel_hi:[1,0,1]
	v_pk_fma_f32 v[26:27], v[8:9], v[34:35], v[26:27] op_sel:[0,1,0] op_sel_hi:[1,1,1]
	v_pk_mul_f32 v[22:23], v[38:39], v[20:21] op_sel:[0,0] op_sel_hi:[1,0]
	v_pk_fma_f32 v[10:11], v[10:11], v[40:41], v[22:23] op_sel_hi:[1,0,1]
	v_pk_fma_f32 v[26:27], v[10:11], v[36:37], v[26:27] op_sel:[0,0,0] op_sel_hi:[1,0,1]
	v_pk_mul_f32 v[24:25], v[38:39], v[20:21] op_sel:[0,1] op_sel_hi:[1,1]
	v_pk_fma_f32 v[12:13], v[12:13], v[40:41], v[24:25] op_sel_hi:[1,0,1]
	v_pk_fma_f32 v[26:27], v[12:13], v[36:37], v[26:27] op_sel:[0,1,0] op_sel_hi:[1,1,1]
	v_pk_fma_f32 v[14:15], v[14:15], v[40:41], v[18:19] op_sel_hi:[1,0,1]
	v_pk_fma_f32 v[16:17], v[16:17], v[40:41], v[20:21] op_sel_hi:[1,0,1]
	v_add_f32_dpp v26, v26, v26 row_ror:8 row_mask:0xf bank_mask:0x3 bound_ctrl:1
	v_add_f32_dpp v26, v27, v27 row_ror:8 row_mask:0xf bank_mask:0xc bound_ctrl:1
	ds_read_b128 v[54:57], v1 offset:47664
	ds_read_b128 v[44:47], v2 offset:42752
	v_add_f32_dpp v26, v26, v26 row_half_mirror row_mask:0xf bank_mask:0xf bound_ctrl:1
	ds_read_b64 v[52:53], v3 offset:46080
	ds_read_b128 v[48:51], v2 offset:43008
	v_add_f32_dpp v26, v26, v26 quad_perm:[1,0,3,2] row_mask:0xf bank_mask:0xf bound_ctrl:1
	s_add_u32 s14, s14, 0x1000
	s_addc_u32 s15, s15, 0
	v_add_f32_dpp v26, v26, v26 quad_perm:[2,3,0,1] row_mask:0xf bank_mask:0xf bound_ctrl:1
	s_cmp_eq_u32 s21, 2
	s_cbranch_scc1 .Lml2_den2_2
.Lml2_back2_2:
	v_mov_b32_dpp v27, v26 row_ror:8 row_mask:0xf bank_mask:0xf bound_ctrl:1
	s_mov_b64 exec, s[18:19]
	v_cvt_pk_bf16_f32 v28, v26, v27
	global_store_dword v4, v28, s[14:15] offset:-4096
	s_mov_b64 exec, -1
	s_waitcnt lgkmcnt(2)
	v_pk_mul_f32 v[18:19], v[44:45], v[54:55] op_sel:[0,1] op_sel_hi:[1,1]
	v_pk_mul_f32 v[20:21], v[46:47], v[54:55] op_sel:[0,1] op_sel_hi:[1,1]
	s_waitcnt lgkmcnt(1)
	v_pk_mul_f32 v[22:23], v[52:53], v[18:19] op_sel:[0,0] op_sel_hi:[1,0]
	v_pk_fma_f32 v[6:7], v[6:7], v[54:55], v[22:23] op_sel_hi:[1,0,1]
	s_waitcnt lgkmcnt(0)
	v_pk_mul_f32 v[26:27], v[6:7], v[48:49] op_sel_hi:[1,0]
	v_pk_mul_f32 v[24:25], v[52:53], v[18:19] op_sel:[0,1] op_sel_hi:[1,1]
	v_pk_fma_f32 v[8:9], v[8:9], v[54:55], v[24:25] op_sel_hi:[1,0,1]
	v_pk_fma_f32 v[26:27], v[8:9], v[48:49], v[26:27] op_sel:[0,1,0] op_sel_hi:[1,1,1]
	v_pk_mul_f32 v[22:23], v[52:53], v[20:21] op_sel:[0,0] op_sel_hi:[1,0]
	v_pk_fma_f32 v[10:11], v[10:11], v[54:55], v[22:23] op_sel_hi:[1,0,1]
	v_pk_fma_f32 v[26:27], v[10:11], v[50:51], v[26:27] op_sel:[0,0,0] op_sel_hi:[1,0,1]
	v_pk_mul_f32 v[24:25], v[52:53], v[20:21] op_sel:[0,1] op_sel_hi:[1,1]
	v_pk_fma_f32 v[12:13], v[12:13], v[54:55], v[24:25] op_sel_hi:[1,0,1]
	v_pk_fma_f32 v[26:27], v[12:13], v[50:51], v[26:27] op_sel:[0,1,0] op_sel_hi:[1,1,1]
	v_pk_fma_f32 v[14:15], v[14:15], v[54:55], v[18:19] op_sel_hi:[1,0,1]
	v_pk_fma_f32 v[16:17], v[16:17], v[54:55], v[20:21] op_sel_hi:[1,0,1]
	v_add_f32_dpp v26, v26, v26 row_ror:8 row_mask:0xf bank_mask:0x3 bound_ctrl:1
	v_add_f32_dpp v26, v27, v27 row_ror:8 row_mask:0xf bank_mask:0xc bound_ctrl:1
	ds_read_b128 v[40:43], v1 offset:47680
	ds_read_b128 v[30:33], v2 offset:43264
	v_add_f32_dpp v26, v26, v26 row_half_mirror row_mask:0xf bank_mask:0xf bound_ctrl:1
	ds_read_b64 v[38:39], v3 offset:46336
	ds_read_b128 v[34:37], v2 offset:43520
	v_add_f32_dpp v26, v26, v26 quad_perm:[1,0,3,2] row_mask:0xf bank_mask:0xf bound_ctrl:1
	s_add_u32 s14, s14, 0x1000
	s_addc_u32 s15, s15, 0
	v_add_f32_dpp v26, v26, v26 quad_perm:[2,3,0,1] row_mask:0xf bank_mask:0xf bound_ctrl:1
	s_cmp_eq_u32 s21, 3
	s_cbranch_scc1 .Lml2_den2_3
.Lml2_back2_3:
	v_mov_b32_dpp v27, v26 row_ror:8 row_mask:0xf bank_mask:0xf bound_ctrl:1
	s_mov_b64 exec, s[18:19]
	v_cvt_pk_bf16_f32 v28, v26, v27
	global_store_dword v4, v28, s[14:15] offset:-4096
	s_mov_b64 exec, -1
	s_waitcnt lgkmcnt(2)
	v_pk_mul_f32 v[18:19], v[30:31], v[40:41] op_sel:[0,1] op_sel_hi:[1,1]
	v_pk_mul_f32 v[20:21], v[32:33], v[40:41] op_sel:[0,1] op_sel_hi:[1,1]
	s_waitcnt lgkmcnt(1)
	v_pk_mul_f32 v[22:23], v[38:39], v[18:19] op_sel:[0,0] op_sel_hi:[1,0]
	v_pk_fma_f32 v[6:7], v[6:7], v[40:41], v[22:23] op_sel_hi:[1,0,1]
	s_waitcnt lgkmcnt(0)
	v_pk_mul_f32 v[26:27], v[6:7], v[34:35] op_sel_hi:[1,0]
	v_pk_mul_f32 v[24:25], v[38:39], v[18:19] op_sel:[0,1] op_sel_hi:[1,1]
	v_pk_fma_f32 v[8:9], v[8:9], v[40:41], v[24:25] op_sel_hi:[1,0,1]
	v_pk_fma_f32 v[26:27], v[8:9], v[34:35], v[26:27] op_sel:[0,1,0] op_sel_hi:[1,1,1]
	v_pk_mul_f32 v[22:23], v[38:39], v[20:21] op_sel:[0,0] op_sel_hi:[1,0]
	v_pk_fma_f32 v[10:11], v[10:11], v[40:41], v[22:23] op_sel_hi:[1,0,1]
	v_pk_fma_f32 v[26:27], v[10:11], v[36:37], v[26:27] op_sel:[0,0,0] op_sel_hi:[1,0,1]
	v_pk_mul_f32 v[24:25], v[38:39], v[20:21] op_sel:[0,1] op_sel_hi:[1,1]
	v_pk_fma_f32 v[12:13], v[12:13], v[40:41], v[24:25] op_sel_hi:[1,0,1]
	v_pk_fma_f32 v[26:27], v[12:13], v[36:37], v[26:27] op_sel:[0,1,0] op_sel_hi:[1,1,1]
	v_pk_fma_f32 v[14:15], v[14:15], v[40:41], v[18:19] op_sel_hi:[1,0,1]
	v_pk_fma_f32 v[16:17], v[16:17], v[40:41], v[20:21] op_sel_hi:[1,0,1]
	v_add_f32_dpp v26, v26, v26 row_ror:8 row_mask:0xf bank_mask:0x3 bound_ctrl:1
	v_add_f32_dpp v26, v27, v27 row_ror:8 row_mask:0xf bank_mask:0xc bound_ctrl:1
	ds_read_b128 v[54:57], v1 offset:47696
	ds_read_b128 v[44:47], v2 offset:43776
	v_add_f32_dpp v26, v26, v26 row_half_mirror row_mask:0xf bank_mask:0xf bound_ctrl:1
	ds_read_b64 v[52:53], v3 offset:46592
	ds_read_b128 v[48:51], v2 offset:44032
	v_add_f32_dpp v26, v26, v26 quad_perm:[1,0,3,2] row_mask:0xf bank_mask:0xf bound_ctrl:1
	s_add_u32 s14, s14, 0x1000
	s_addc_u32 s15, s15, 0
	v_add_f32_dpp v26, v26, v26 quad_perm:[2,3,0,1] row_mask:0xf bank_mask:0xf bound_ctrl:1
	s_cmp_eq_u32 s21, 4
	s_cbranch_scc1 .Lml2_den2_4
.Lml2_back2_4:
	v_mov_b32_dpp v27, v26 row_ror:8 row_mask:0xf bank_mask:0xf bound_ctrl:1
	s_mov_b64 exec, s[18:19]
	v_cvt_pk_bf16_f32 v28, v26, v27
	global_store_dword v4, v28, s[14:15] offset:-4096
	s_mov_b64 exec, -1
	s_waitcnt lgkmcnt(2)
	v_pk_mul_f32 v[18:19], v[44:45], v[54:55] op_sel:[0,1] op_sel_hi:[1,1]
	v_pk_mul_f32 v[20:21], v[46:47], v[54:55] op_sel:[0,1] op_sel_hi:[1,1]
	s_waitcnt lgkmcnt(1)
	v_pk_mul_f32 v[22:23], v[52:53], v[18:19] op_sel:[0,0] op_sel_hi:[1,0]
	v_pk_fma_f32 v[6:7], v[6:7], v[54:55], v[22:23] op_sel_hi:[1,0,1]
	s_waitcnt lgkmcnt(0)
	v_pk_mul_f32 v[26:27], v[6:7], v[48:49] op_sel_hi:[1,0]
	v_pk_mul_f32 v[24:25], v[52:53], v[18:19] op_sel:[0,1] op_sel_hi:[1,1]
	v_pk_fma_f32 v[8:9], v[8:9], v[54:55], v[24:25] op_sel_hi:[1,0,1]
	v_pk_fma_f32 v[26:27], v[8:9], v[48:49], v[26:27] op_sel:[0,1,0] op_sel_hi:[1,1,1]
	v_pk_mul_f32 v[22:23], v[52:53], v[20:21] op_sel:[0,0] op_sel_hi:[1,0]
	v_pk_fma_f32 v[10:11], v[10:11], v[54:55], v[22:23] op_sel_hi:[1,0,1]
	v_pk_fma_f32 v[26:27], v[10:11], v[50:51], v[26:27] op_sel:[0,0,0] op_sel_hi:[1,0,1]
	v_pk_mul_f32 v[24:25], v[52:53], v[20:21] op_sel:[0,1] op_sel_hi:[1,1]
	v_pk_fma_f32 v[12:13], v[12:13], v[54:55], v[24:25] op_sel_hi:[1,0,1]
	v_pk_fma_f32 v[26:27], v[12:13], v[50:51], v[26:27] op_sel:[0,1,0] op_sel_hi:[1,1,1]
	v_pk_fma_f32 v[14:15], v[14:15], v[54:55], v[18:19] op_sel_hi:[1,0,1]
	v_pk_fma_f32 v[16:17], v[16:17], v[54:55], v[20:21] op_sel_hi:[1,0,1]
	v_add_f32_dpp v26, v26, v26 row_ror:8 row_mask:0xf bank_mask:0x3 bound_ctrl:1
	v_add_f32_dpp v26, v27, v27 row_ror:8 row_mask:0xf bank_mask:0xc bound_ctrl:1
	ds_read_b128 v[40:43], v1 offset:47712
	ds_read_b128 v[30:33], v2 offset:44288
	v_add_f32_dpp v26, v26, v26 row_half_mirror row_mask:0xf bank_mask:0xf bound_ctrl:1
	ds_read_b64 v[38:39], v3 offset:46848
	ds_read_b128 v[34:37], v2 offset:44544
	v_add_f32_dpp v26, v26, v26 quad_perm:[1,0,3,2] row_mask:0xf bank_mask:0xf bound_ctrl:1
	s_add_u32 s14, s14, 0x1000
	s_addc_u32 s15, s15, 0
	v_add_f32_dpp v26, v26, v26 quad_perm:[2,3,0,1] row_mask:0xf bank_mask:0xf bound_ctrl:1
	s_cmp_eq_u32 s21, 5
	s_cbranch_scc1 .Lml2_den2_5
.Lml2_back2_5:
	v_mov_b32_dpp v27, v26 row_ror:8 row_mask:0xf bank_mask:0xf bound_ctrl:1
	s_mov_b64 exec, s[18:19]
	v_cvt_pk_bf16_f32 v28, v26, v27
	global_store_dword v4, v28, s[14:15] offset:-4096
	s_mov_b64 exec, -1
	s_waitcnt lgkmcnt(2)
	v_pk_mul_f32 v[18:19], v[30:31], v[40:41] op_sel:[0,1] op_sel_hi:[1,1]
	v_pk_mul_f32 v[20:21], v[32:33], v[40:41] op_sel:[0,1] op_sel_hi:[1,1]
	s_waitcnt lgkmcnt(1)
	v_pk_mul_f32 v[22:23], v[38:39], v[18:19] op_sel:[0,0] op_sel_hi:[1,0]
	v_pk_fma_f32 v[6:7], v[6:7], v[40:41], v[22:23] op_sel_hi:[1,0,1]
	s_waitcnt lgkmcnt(0)
	v_pk_mul_f32 v[26:27], v[6:7], v[34:35] op_sel_hi:[1,0]
	v_pk_mul_f32 v[24:25], v[38:39], v[18:19] op_sel:[0,1] op_sel_hi:[1,1]
	v_pk_fma_f32 v[8:9], v[8:9], v[40:41], v[24:25] op_sel_hi:[1,0,1]
	v_pk_fma_f32 v[26:27], v[8:9], v[34:35], v[26:27] op_sel:[0,1,0] op_sel_hi:[1,1,1]
	v_pk_mul_f32 v[22:23], v[38:39], v[20:21] op_sel:[0,0] op_sel_hi:[1,0]
	v_pk_fma_f32 v[10:11], v[10:11], v[40:41], v[22:23] op_sel_hi:[1,0,1]
	v_pk_fma_f32 v[26:27], v[10:11], v[36:37], v[26:27] op_sel:[0,0,0] op_sel_hi:[1,0,1]
	v_pk_mul_f32 v[24:25], v[38:39], v[20:21] op_sel:[0,1] op_sel_hi:[1,1]
	v_pk_fma_f32 v[12:13], v[12:13], v[40:41], v[24:25] op_sel_hi:[1,0,1]
	v_pk_fma_f32 v[26:27], v[12:13], v[36:37], v[26:27] op_sel:[0,1,0] op_sel_hi:[1,1,1]
	v_pk_fma_f32 v[14:15], v[14:15], v[40:41], v[18:19] op_sel_hi:[1,0,1]
	v_pk_fma_f32 v[16:17], v[16:17], v[40:41], v[20:21] op_sel_hi:[1,0,1]
	v_add_f32_dpp v26, v26, v26 row_ror:8 row_mask:0xf bank_mask:0x3 bound_ctrl:1
	v_add_f32_dpp v26, v27, v27 row_ror:8 row_mask:0xf bank_mask:0xc bound_ctrl:1
	ds_read_b128 v[54:57], v1 offset:47728
	ds_read_b128 v[44:47], v2 offset:44800
	v_add_f32_dpp v26, v26, v26 row_half_mirror row_mask:0xf bank_mask:0xf bound_ctrl:1
	ds_read_b64 v[52:53], v3 offset:47104
	ds_read_b128 v[48:51], v2 offset:45056
	v_add_f32_dpp v26, v26, v26 quad_perm:[1,0,3,2] row_mask:0xf bank_mask:0xf bound_ctrl:1
	s_add_u32 s14, s14, 0x1000
	s_addc_u32 s15, s15, 0
	v_add_f32_dpp v26, v26, v26 quad_perm:[2,3,0,1] row_mask:0xf bank_mask:0xf bound_ctrl:1
	s_cmp_eq_u32 s21, 6
	s_cbranch_scc1 .Lml2_den2_6
.Lml2_back2_6:
	v_mov_b32_dpp v27, v26 row_ror:8 row_mask:0xf bank_mask:0xf bound_ctrl:1
	s_mov_b64 exec, s[18:19]
	v_cvt_pk_bf16_f32 v28, v26, v27
	global_store_dword v4, v28, s[14:15] offset:-4096
	s_mov_b64 exec, -1
	s_waitcnt lgkmcnt(2)
	v_pk_mul_f32 v[18:19], v[44:45], v[54:55] op_sel:[0,1] op_sel_hi:[1,1]
	v_pk_mul_f32 v[20:21], v[46:47], v[54:55] op_sel:[0,1] op_sel_hi:[1,1]
	s_waitcnt lgkmcnt(1)
	v_pk_mul_f32 v[22:23], v[52:53], v[18:19] op_sel:[0,0] op_sel_hi:[1,0]
	v_pk_fma_f32 v[6:7], v[6:7], v[54:55], v[22:23] op_sel_hi:[1,0,1]
	s_waitcnt lgkmcnt(0)
	v_pk_mul_f32 v[26:27], v[6:7], v[48:49] op_sel_hi:[1,0]
	v_pk_mul_f32 v[24:25], v[52:53], v[18:19] op_sel:[0,1] op_sel_hi:[1,1]
	v_pk_fma_f32 v[8:9], v[8:9], v[54:55], v[24:25] op_sel_hi:[1,0,1]
	v_pk_fma_f32 v[26:27], v[8:9], v[48:49], v[26:27] op_sel:[0,1,0] op_sel_hi:[1,1,1]
	v_pk_mul_f32 v[22:23], v[52:53], v[20:21] op_sel:[0,0] op_sel_hi:[1,0]
	v_pk_fma_f32 v[10:11], v[10:11], v[54:55], v[22:23] op_sel_hi:[1,0,1]
	v_pk_fma_f32 v[26:27], v[10:11], v[50:51], v[26:27] op_sel:[0,0,0] op_sel_hi:[1,0,1]
	v_pk_mul_f32 v[24:25], v[52:53], v[20:21] op_sel:[0,1] op_sel_hi:[1,1]
	v_pk_fma_f32 v[12:13], v[12:13], v[54:55], v[24:25] op_sel_hi:[1,0,1]
	v_pk_fma_f32 v[26:27], v[12:13], v[50:51], v[26:27] op_sel:[0,1,0] op_sel_hi:[1,1,1]
	v_pk_fma_f32 v[14:15], v[14:15], v[54:55], v[18:19] op_sel_hi:[1,0,1]
	v_pk_fma_f32 v[16:17], v[16:17], v[54:55], v[20:21] op_sel_hi:[1,0,1]
	v_add_f32_dpp v26, v26, v26 row_ror:8 row_mask:0xf bank_mask:0x3 bound_ctrl:1
	v_add_f32_dpp v26, v27, v27 row_ror:8 row_mask:0xf bank_mask:0xc bound_ctrl:1
	ds_read_b128 v[40:43], v1 offset:14848
	ds_read_b128 v[30:33], v2 offset:8448
	v_add_f32_dpp v26, v26, v26 row_half_mirror row_mask:0xf bank_mask:0xf bound_ctrl:1
	ds_read_b64 v[38:39], v3 offset:12544
	ds_read_b128 v[34:37], v2 offset:8704
	v_add_f32_dpp v26, v26, v26 quad_perm:[1,0,3,2] row_mask:0xf bank_mask:0xf bound_ctrl:1
	s_add_u32 s14, s14, 0x1000
	s_addc_u32 s15, s15, 0
	v_add_f32_dpp v26, v26, v26 quad_perm:[2,3,0,1] row_mask:0xf bank_mask:0xf bound_ctrl:1
	s_cmp_eq_u32 s21, 7
	s_cbranch_scc1 .Lml2_den2_7
.Lml2_back2_7:
	v_mov_b32_dpp v27, v26 row_ror:8 row_mask:0xf bank_mask:0xf bound_ctrl:1
	s_mov_b64 exec, s[18:19]
	v_cvt_pk_bf16_f32 v28, v26, v27
	global_store_dword v4, v28, s[14:15] offset:-4096
	s_mov_b64 exec, -1
	s_waitcnt vmcnt(8)
	v_lshlrev_b32_e32 v88, 16, v80
	v_lshlrev_b32_e32 v89, 16, v81
	v_and_b32_e32 v90, s17, v80
	v_and_b32_e32 v91, s17, v81
	v_lshlrev_b32_e32 v92, 16, v82
	v_and_b32_e32 v93, s17, v82
	v_lshlrev_b32_e32 v94, 16, v83
	v_and_b32_e32 v95, s17, v83
	v_lshlrev_b32_e32 v96, 16, v84
	v_and_b32_e32 v97, s17, v84
	ds_write_b128 v69, v[88:91] offset:16640
	ds_write_b64 v70, v[92:93] offset:16640
	ds_write_b64 v71, v[94:95] offset:16640
	ds_write_b64 v71, v[96:97] offset:16768
	ds_write_b32 v72, v85 offset:16640
	s_cmp_lg_u32 s36, 4
	s_cbranch_scc1 .Lml2_nsc4
	v_mov_b32_e32 v98, v87
	s_nop 1
	v_add_f32_dpp v98, v98, v98 row_shr:1 row_mask:0xf bank_mask:0xf bound_ctrl:1
	s_nop 1
	v_add_f32_dpp v98, v98, v98 row_shr:2 row_mask:0xf bank_mask:0xf bound_ctrl:1
	s_nop 1
	v_add_f32_dpp v98, v98, v98 row_shr:4 row_mask:0xf bank_mask:0xf bound_ctrl:1
	s_nop 1
	v_sub_f32_e32 v99, v86, v98
	s_nop 1
	v_max_f32_dpp v99, v99, v99 row_shr:1 row_mask:0xf bank_mask:0xf
	s_nop 1
	v_max_f32_dpp v99, v99, v99 row_shr:2 row_mask:0xf bank_mask:0xf
	s_nop 1
	v_max_f32_dpp v99, v99, v99 row_shr:4 row_mask:0xf bank_mask:0xf
	s_nop 1
	v_max_f32_e32 v99, v99, v0
	v_add_f32_e32 v103, v98, v99
	v_mov_b32_e32 v105, v0
	s_nop 1
	v_mov_b32_dpp v105, v103 row_shr:1 row_mask:0xf bank_mask:0xf
	v_sub_f32_e32 v104, v86, v103
	v_add_f32_e32 v105, v87, v105
	v_fma_f32 v104, v104, s29, v29
	v_sub_f32_e32 v105, v105, v103
	v_exp_f32_e32 v101, v104
	v_mul_f32_e32 v105, s29, v105
	v_mul_f32_e32 v104, 0xbfb8aa3b, v103
	v_exp_f32_e32 v100, v105
	v_exp_f32_e32 v102, v104
	v_readlane_b32 s4, v103, 7
	s_nop 3
	v_mov_b32_e32 v0, s4
	ds_write_b128 v73, v[100:103] offset:16640
